# RG-LRU phase: next result tile's weight fragments requested before the current tile's gate math
# baseline (speedup 1.0000x reference)
.LBB0_439:
	s_or_b64 exec, exec, s[50:51]
	s_waitcnt lgkmcnt(0)
	s_barrier
	ds_read_b128 v[56:59], v176 offset:11808
	ds_read_b128 v[52:55], v176 offset:11872
	ds_read_b128 v[48:51], v176 offset:11936
	ds_read_b128 v[24:27], v188 offset:39536
	ds_read_b128 v[28:31], v188 offset:49520
	s_waitcnt lgkmcnt(1)
	v_mfma_f32_16x16x32_bf16 v[24:27], v[24:27], v[56:59], 0
	ds_read_b128 v[32:35], v188 offset:39600
	ds_read_b128 v[36:39], v188 offset:49584
	s_waitcnt lgkmcnt(2)
	v_mfma_f32_16x16x32_bf16 v[28:31], v[28:31], v[56:59], 0
	s_waitcnt lgkmcnt(1)
	v_mfma_f32_16x16x32_bf16 v[24:27], v[32:35], v[52:55], v[24:27]
	ds_read_b128 v[32:35], v188 offset:39664
	ds_read_b128 v[40:43], v188 offset:49648
	s_waitcnt lgkmcnt(2)
	v_mfma_f32_16x16x32_bf16 v[28:31], v[36:39], v[52:55], v[28:31]
	s_waitcnt lgkmcnt(1)
	v_mfma_f32_16x16x32_bf16 v[36:39], v[32:35], v[48:51], v[24:27]
	s_waitcnt lgkmcnt(0)
	v_mfma_f32_16x16x32_bf16 v[24:27], v[40:43], v[48:51], v[28:31]
	ds_read_b128 v[40:43], v150 offset:37408
	s_nop 2
	ds_read_b128 v[28:31], v150 offset:37600
	ds_read_b128 v[44:47], v150 offset:37792
	ds_read_b128 v[32:35], v189 offset:25120
	ds_read_b128 v[220:223], v188 offset:42864
	ds_read_b128 v[224:227], v188 offset:52848
	ds_read_b128 v[228:231], v188 offset:42928
	ds_read_b128 v[232:235], v188 offset:52912
	s_waitcnt lgkmcnt(7)
	v_add_f32_e32 v236, v36, v40
	v_add_f32_e32 v237, v37, v41
	v_add_f32_e32 v238, v38, v42
	v_add_f32_e32 v239, v39, v43
	v_mul_f32_e32 v236, 0xbfb8aa3b, v236
	v_mul_f32_e32 v237, 0xbfb8aa3b, v237
	v_mul_f32_e32 v238, 0xbfb8aa3b, v238
	v_mul_f32_e32 v239, 0xbfb8aa3b, v239
	v_exp_f32_e32 v236, v236
	v_exp_f32_e32 v237, v237
	v_exp_f32_e32 v238, v238
	v_exp_f32_e32 v239, v239
	v_add_f32_e32 v236, 1.0, v236
	v_add_f32_e32 v237, 1.0, v237
	v_add_f32_e32 v238, 1.0, v238
	v_add_f32_e32 v239, 1.0, v239
	v_rcp_f32_e32 v236, v236
	v_rcp_f32_e32 v237, v237
	v_rcp_f32_e32 v238, v238
	v_rcp_f32_e32 v239, v239
	s_waitcnt lgkmcnt(5)
	v_mul_f32_e32 v240, v44, v236
	v_mul_f32_e32 v241, v45, v237
	v_mul_f32_e32 v242, v46, v238
	v_mul_f32_e32 v243, v47, v239
	v_mul_f32_e32 v236, 0x3fb8aa3b, v240
	v_mul_f32_e32 v237, 0x3fb8aa3b, v241
	v_mul_f32_e32 v238, 0x3fb8aa3b, v242
	v_mul_f32_e32 v239, 0x3fb8aa3b, v243
	v_exp_f32_e32 v0, v236
	v_exp_f32_e32 v3, v237
	v_exp_f32_e32 v209, v238
	v_exp_f32_e32 v213, v239
	v_add_f32_e32 v240, v240, v240
	v_add_f32_e32 v241, v241, v241
	v_add_f32_e32 v242, v242, v242
	v_add_f32_e32 v243, v243, v243
	v_fmamk_f32 v236, v240, 0x3d2aaaab, v177
	v_fmamk_f32 v237, v241, 0x3d2aaaab, v177
	v_fmamk_f32 v238, v242, 0x3d2aaaab, v177
	v_fmamk_f32 v239, v243, 0x3d2aaaab, v177
	v_fma_f32 v236, v240, v236, 0.5
	v_fma_f32 v237, v241, v237, 0.5
	v_fma_f32 v238, v242, v238, 0.5
	v_fma_f32 v239, v243, v239, 0.5
	v_fma_f32 v236, v240, v236, 1.0
	v_fma_f32 v237, v241, v237, 1.0
	v_fma_f32 v238, v242, v238, 1.0
	v_fma_f32 v239, v243, v239, 1.0
	v_mul_f32_e64 v236, v236, -v240
	v_mul_f32_e64 v237, v237, -v241
	v_mul_f32_e64 v238, v238, -v242
	v_mul_f32_e64 v239, v239, -v243
	v_cmp_nlt_f32_e64 s[0:1], s79, v240
	v_cmp_nlt_f32_e64 s[50:51], s79, v241
	v_fma_f32 v244, -v0, v0, 1.0
	v_fma_f32 v245, -v3, v3, 1.0
	v_cndmask_b32_e64 v2, v236, v244, s[0:1]
	v_cndmask_b32_e64 v206, v237, v245, s[50:51]
	v_cmp_nlt_f32_e64 s[0:1], s79, v242
	v_cmp_nlt_f32_e64 s[50:51], s79, v243
	v_fma_f32 v246, -v209, v209, 1.0
	v_fma_f32 v247, -v213, v213, 1.0
	v_cndmask_b32_e64 v210, v238, v246, s[0:1]
	v_cndmask_b32_e64 v214, v239, v247, s[50:51]
	s_waitcnt lgkmcnt(3)
	v_mfma_f32_16x16x32_bf16 v[36:39], v[220:223], v[56:59], 0
	s_waitcnt lgkmcnt(2)
	v_mfma_f32_16x16x32_bf16 v[40:43], v[224:227], v[56:59], 0
	s_waitcnt lgkmcnt(1)
	v_mfma_f32_16x16x32_bf16 v[36:39], v[228:231], v[52:55], v[36:39]
	ds_read_b128 v[44:47], v188 offset:42992
	ds_read_b128 v[64:67], v188 offset:52976
	s_waitcnt lgkmcnt(2)
	v_mfma_f32_16x16x32_bf16 v[40:43], v[232:235], v[52:55], v[40:43]
	s_waitcnt lgkmcnt(1)
	v_mfma_f32_16x16x32_bf16 v[60:63], v[44:47], v[48:51], v[36:39]
	s_waitcnt lgkmcnt(0)
	v_mfma_f32_16x16x32_bf16 v[36:39], v[64:67], v[48:51], v[40:43]
	ds_read_b128 v[64:67], v150 offset:37472
	s_nop 2
	ds_read_b128 v[40:43], v150 offset:37664
	ds_read_b128 v[68:71], v150 offset:37856
	ds_read_b128 v[44:47], v189 offset:25184
	ds_read_b128 v[220:223], v188 offset:46192
	ds_read_b128 v[224:227], v188 offset:56176
	ds_read_b128 v[228:231], v188 offset:46256
	ds_read_b128 v[232:235], v188 offset:56240
	s_waitcnt lgkmcnt(7)
	v_add_f32_e32 v236, v60, v64
	v_add_f32_e32 v237, v61, v65
	v_add_f32_e32 v238, v62, v66
	v_add_f32_e32 v239, v63, v67
	v_mul_f32_e32 v236, 0xbfb8aa3b, v236
	v_mul_f32_e32 v237, 0xbfb8aa3b, v237
	v_mul_f32_e32 v238, 0xbfb8aa3b, v238
	v_mul_f32_e32 v239, 0xbfb8aa3b, v239
	v_exp_f32_e32 v236, v236
	v_exp_f32_e32 v237, v237
	v_exp_f32_e32 v238, v238
	v_exp_f32_e32 v239, v239
	v_add_f32_e32 v236, 1.0, v236
	v_add_f32_e32 v237, 1.0, v237
	v_add_f32_e32 v238, 1.0, v238
	v_add_f32_e32 v239, 1.0, v239
	v_rcp_f32_e32 v236, v236
	v_rcp_f32_e32 v237, v237
	v_rcp_f32_e32 v238, v238
	v_rcp_f32_e32 v239, v239
	s_waitcnt lgkmcnt(5)
	v_mul_f32_e32 v240, v68, v236
	v_mul_f32_e32 v241, v69, v237
	v_mul_f32_e32 v242, v70, v238
	v_mul_f32_e32 v243, v71, v239
	v_mul_f32_e32 v236, 0x3fb8aa3b, v240
	v_mul_f32_e32 v237, 0x3fb8aa3b, v241
	v_mul_f32_e32 v238, 0x3fb8aa3b, v242
	v_mul_f32_e32 v239, 0x3fb8aa3b, v243
	v_exp_f32_e32 v207, v236
	v_exp_f32_e32 v211, v237
	v_exp_f32_e32 v215, v238
	v_exp_f32_e32 v217, v239
	v_add_f32_e32 v240, v240, v240
	v_add_f32_e32 v241, v241, v241
	v_add_f32_e32 v242, v242, v242
	v_add_f32_e32 v243, v243, v243
	v_fmamk_f32 v236, v240, 0x3d2aaaab, v177
	v_fmamk_f32 v237, v241, 0x3d2aaaab, v177
	v_fmamk_f32 v238, v242, 0x3d2aaaab, v177
	v_fmamk_f32 v239, v243, 0x3d2aaaab, v177
	v_fma_f32 v236, v240, v236, 0.5
	v_fma_f32 v237, v241, v237, 0.5
	v_fma_f32 v238, v242, v238, 0.5
	v_fma_f32 v239, v243, v239, 0.5
	v_fma_f32 v236, v240, v236, 1.0
	v_fma_f32 v237, v241, v237, 1.0
	v_fma_f32 v238, v242, v238, 1.0
	v_fma_f32 v239, v243, v239, 1.0
	v_mul_f32_e64 v236, v236, -v240
	v_mul_f32_e64 v237, v237, -v241
	v_mul_f32_e64 v238, v238, -v242
	v_mul_f32_e64 v239, v239, -v243
	v_cmp_nlt_f32_e64 s[0:1], s79, v240
	v_cmp_nlt_f32_e64 s[50:51], s79, v241
	v_fma_f32 v244, -v207, v207, 1.0
	v_fma_f32 v245, -v211, v211, 1.0
	v_cndmask_b32_e64 v208, v236, v244, s[0:1]
	v_cndmask_b32_e64 v212, v237, v245, s[50:51]
	v_cmp_nlt_f32_e64 s[0:1], s79, v242
	v_cmp_nlt_f32_e64 s[50:51], s79, v243
	v_fma_f32 v246, -v215, v215, 1.0
	v_fma_f32 v247, -v217, v217, 1.0
	v_cndmask_b32_e64 v216, v238, v246, s[0:1]
	v_cndmask_b32_e64 v218, v239, v247, s[50:51]
	s_waitcnt lgkmcnt(3)
	v_mfma_f32_16x16x32_bf16 v[60:63], v[220:223], v[56:59], 0
	s_waitcnt lgkmcnt(2)
	v_mfma_f32_16x16x32_bf16 v[56:59], v[224:227], v[56:59], 0
	s_waitcnt lgkmcnt(1)
	v_mfma_f32_16x16x32_bf16 v[60:63], v[228:231], v[52:55], v[60:63]
	s_waitcnt lgkmcnt(0)
	s_nop 1
	v_mfma_f32_16x16x32_bf16 v[52:55], v[232:235], v[52:55], v[56:59]
	s_nop 2
	ds_read_b128 v[56:59], v188 offset:46320
	ds_read_b128 v[64:67], v188 offset:56304
	s_waitcnt lgkmcnt(1)
	v_mfma_f32_16x16x32_bf16 v[60:63], v[56:59], v[48:51], v[60:63]
	s_waitcnt lgkmcnt(0)
	v_mfma_f32_16x16x32_bf16 v[48:51], v[64:67], v[48:51], v[52:55]
	ds_read_b128 v[64:67], v150 offset:37536
	s_nop 1
	ds_read_b128 v[52:55], v150 offset:37728
	ds_read_b128 v[68:71], v150 offset:37920
	ds_read_b128 v[56:59], v189 offset:25248
	s_waitcnt lgkmcnt(3)
	v_add_f32_e32 v236, v60, v64
	v_add_f32_e32 v237, v61, v65
	v_add_f32_e32 v238, v62, v66
	v_add_f32_e32 v239, v63, v67
	v_mul_f32_e32 v236, 0xbfb8aa3b, v236
	v_mul_f32_e32 v237, 0xbfb8aa3b, v237
	v_mul_f32_e32 v238, 0xbfb8aa3b, v238
	v_mul_f32_e32 v239, 0xbfb8aa3b, v239
	v_exp_f32_e32 v236, v236
	v_exp_f32_e32 v237, v237
	v_exp_f32_e32 v238, v238
	v_exp_f32_e32 v239, v239
	v_add_f32_e32 v236, 1.0, v236
	v_add_f32_e32 v237, 1.0, v237
	v_add_f32_e32 v238, 1.0, v238
	v_add_f32_e32 v239, 1.0, v239
	v_rcp_f32_e32 v236, v236
	v_rcp_f32_e32 v237, v237
	v_rcp_f32_e32 v238, v238
	v_rcp_f32_e32 v239, v239
	s_waitcnt lgkmcnt(1)
	v_mul_f32_e32 v240, v68, v236
	v_mul_f32_e32 v241, v69, v237
	v_mul_f32_e32 v242, v70, v238
	v_mul_f32_e32 v243, v71, v239
	v_mul_f32_e32 v236, 0x3fb8aa3b, v240
	v_mul_f32_e32 v237, 0x3fb8aa3b, v241
	v_mul_f32_e32 v238, 0x3fb8aa3b, v242
	v_mul_f32_e32 v239, 0x3fb8aa3b, v243
	v_exp_f32_e32 v60, v236
	v_exp_f32_e32 v61, v237
	v_exp_f32_e32 v62, v238
	v_exp_f32_e32 v63, v239
	v_add_f32_e32 v240, v240, v240
	v_add_f32_e32 v241, v241, v241
	v_add_f32_e32 v242, v242, v242
	v_add_f32_e32 v243, v243, v243
	v_fmamk_f32 v236, v240, 0x3d2aaaab, v177
	v_fmamk_f32 v237, v241, 0x3d2aaaab, v177
	v_fmamk_f32 v238, v242, 0x3d2aaaab, v177
	v_fmamk_f32 v239, v243, 0x3d2aaaab, v177
	v_fma_f32 v236, v240, v236, 0.5
	v_fma_f32 v237, v241, v237, 0.5
	v_fma_f32 v238, v242, v238, 0.5
	v_fma_f32 v239, v243, v239, 0.5
	v_fma_f32 v236, v240, v236, 1.0
	v_fma_f32 v237, v241, v237, 1.0
	v_fma_f32 v238, v242, v238, 1.0
	v_fma_f32 v239, v243, v239, 1.0
	v_mul_f32_e64 v236, v236, -v240
	v_mul_f32_e64 v237, v237, -v241
	v_mul_f32_e64 v238, v238, -v242
	v_mul_f32_e64 v239, v239, -v243
	v_cmp_nlt_f32_e64 s[0:1], s79, v240
	v_cmp_nlt_f32_e64 s[50:51], s79, v241
	v_fma_f32 v244, -v60, v60, 1.0
	v_fma_f32 v245, -v61, v61, 1.0
	v_cndmask_b32_e64 v64, v236, v244, s[0:1]
	v_cndmask_b32_e64 v65, v237, v245, s[50:51]
	v_cmp_nlt_f32_e64 s[0:1], s79, v242
	v_cmp_nlt_f32_e64 s[50:51], s79, v243
	v_fma_f32 v246, -v62, v62, 1.0
	v_fma_f32 v247, -v63, v63, 1.0
	v_cndmask_b32_e64 v66, v238, v246, s[0:1]
	v_cndmask_b32_e64 v67, v239, v247, s[50:51]
	v_add_f32_e32 v27, v27, v31
	v_mul_f32_e32 v27, 0xbfb8aa3b, v27
	v_exp_f32_e32 v31, v27
	v_sqrt_f32_e32 v69, v214
	v_or_b32_e32 v68, s33, v142
	v_add_f32_e32 v26, v26, v30
	v_add_f32_e32 v31, 1.0, v31
	v_rcp_f32_e32 v31, v31
	v_cmp_ne_u32_e64 s[0:1], 0, v68
	v_mul_f32_e32 v26, 0xbfb8aa3b, v26
	s_or_b64 s[50:51], s[30:31], s[0:1]
	v_exp_f32_e32 v26, v26
	v_cndmask_b32_e64 v68, 1.0, v69, s[50:51]
	v_mul_f32_e32 v31, v31, v68
	v_mul_f32_e32 v30, v35, v31
	v_cndmask_b32_e64 v31, v30, 0, s[46:47]
	v_sqrt_f32_e32 v30, v210
	v_add_f32_e32 v26, 1.0, v26
	v_rcp_f32_e32 v35, v26
	v_add_f32_e32 v25, v25, v29
	v_mul_f32_e32 v25, 0xbfb8aa3b, v25
	v_exp_f32_e32 v25, v25
	v_cndmask_b32_e64 v30, 1.0, v30, s[50:51]
	v_mul_f32_e32 v29, v35, v30
	v_mul_f32_e32 v29, v34, v29
	v_add_f32_e32 v24, v24, v28
	v_cndmask_b32_e64 v30, v29, 0, s[46:47]
	v_add_f32_e32 v25, 1.0, v25
	v_sqrt_f32_e32 v29, v206
	v_mul_f32_e32 v24, 0xbfb8aa3b, v24
	v_rcp_f32_e32 v25, v25
	v_exp_f32_e32 v24, v24
	v_cndmask_b32_e64 v28, 1.0, v29, s[50:51]
	v_cndmask_b32_e64 v3, v3, 1.0, s[46:47]
	v_mul_f32_e32 v25, v25, v28
	v_add_f32_e32 v24, 1.0, v24
	v_sqrt_f32_e32 v28, v2
	v_rcp_f32_e32 v24, v24
	v_cndmask_b32_e64 v2, v0, 1.0, s[46:47]
	v_mul_f32_e32 v25, v33, v25
	v_cndmask_b32_e64 v0, 1.0, v28, s[50:51]
	v_mul_f32_e32 v0, v24, v0
	v_mul_f32_e32 v0, v32, v0
	v_cndmask_b32_e64 v25, v25, 0, s[46:47]
	v_cndmask_b32_e64 v24, v0, 0, s[46:47]
	v_mov_b32_e32 v28, 1.0
	v_mov_b32_e32 v32, v1
	v_mov_b32_e32 v29, 1.0
	v_mov_b32_e32 v33, v1
	v_mov_b32_dpp v28, v2 row_shr:1 row_mask:0xf bank_mask:0xf
	v_mov_b32_dpp v32, v24 row_shr:1 row_mask:0xf bank_mask:0xf
	v_mov_b32_dpp v29, v3 row_shr:1 row_mask:0xf bank_mask:0xf
	v_mov_b32_dpp v33, v25 row_shr:1 row_mask:0xf bank_mask:0xf
	v_pk_mul_f32 v[28:29], v[2:3], v[28:29]
	v_pk_fma_f32 v[2:3], v[2:3], v[32:33], v[24:25]
	v_mov_b32_e32 v24, v1
	v_mov_b32_e32 v25, v1
	v_mov_b32_e32 v34, 1.0
	v_mov_b32_dpp v24, v2 row_shr:2 row_mask:0xf bank_mask:0xf
	v_mov_b32_e32 v35, 1.0
	v_mov_b32_dpp v25, v3 row_shr:2 row_mask:0xf bank_mask:0xf
	v_mov_b32_dpp v34, v28 row_shr:2 row_mask:0xf bank_mask:0xf
	v_mov_b32_dpp v35, v29 row_shr:2 row_mask:0xf bank_mask:0xf
	v_pk_fma_f32 v[2:3], v[28:29], v[24:25], v[2:3]
	v_mov_b32_e32 v24, v1
	v_mov_b32_e32 v25, v1
	v_pk_mul_f32 v[32:33], v[28:29], v[34:35]
	v_mov_b32_e32 v34, 1.0
	v_mov_b32_dpp v24, v2 row_shr:4 row_mask:0xf bank_mask:0xf
	v_mov_b32_e32 v35, 1.0
	v_mov_b32_dpp v25, v3 row_shr:4 row_mask:0xf bank_mask:0xf
	v_mov_b32_dpp v34, v32 row_shr:4 row_mask:0xf bank_mask:0xf
	v_mov_b32_dpp v35, v33 row_shr:4 row_mask:0xf bank_mask:0xf
	v_pk_fma_f32 v[2:3], v[32:33], v[24:25], v[2:3]
	v_mov_b32_e32 v24, v1
	v_mov_b32_e32 v25, v1
	v_pk_mul_f32 v[28:29], v[32:33], v[34:35]
	v_mov_b32_dpp v24, v2 row_shr:8 row_mask:0xf bank_mask:0xf
	v_mov_b32_dpp v25, v3 row_shr:8 row_mask:0xf bank_mask:0xf
	v_cndmask_b32_e64 v27, v213, 1.0, s[46:47]
	v_cndmask_b32_e64 v26, v209, 1.0, s[46:47]
	v_mov_b32_e32 v34, 1.0
	v_mov_b32_e32 v35, 1.0
	v_pk_fma_f32 v[24:25], v[28:29], v[24:25], v[2:3]
	v_mov_b32_e32 v2, 1.0
	v_mov_b32_e32 v32, v1
	v_mov_b32_e32 v3, 1.0
	v_mov_b32_e32 v33, v1
	v_mov_b32_dpp v34, v28 row_shr:8 row_mask:0xf bank_mask:0xf
	v_mov_b32_dpp v35, v29 row_shr:8 row_mask:0xf bank_mask:0xf
	v_mov_b32_dpp v2, v26 row_shr:1 row_mask:0xf bank_mask:0xf
	v_mov_b32_dpp v32, v30 row_shr:1 row_mask:0xf bank_mask:0xf
	v_mov_b32_dpp v3, v27 row_shr:1 row_mask:0xf bank_mask:0xf
	v_mov_b32_dpp v33, v31 row_shr:1 row_mask:0xf bank_mask:0xf
	v_pk_mul_f32 v[28:29], v[28:29], v[34:35]
	v_pk_mul_f32 v[2:3], v[26:27], v[2:3]
	v_mov_b32_e32 v34, 1.0
	v_pk_fma_f32 v[26:27], v[26:27], v[32:33], v[30:31]
	v_mov_b32_e32 v30, v1
	v_mov_b32_e32 v35, 1.0
	v_mov_b32_e32 v31, v1
	v_mov_b32_dpp v34, v2 row_shr:2 row_mask:0xf bank_mask:0xf
	v_mov_b32_dpp v30, v26 row_shr:2 row_mask:0xf bank_mask:0xf
	v_mov_b32_dpp v35, v3 row_shr:2 row_mask:0xf bank_mask:0xf
	v_mov_b32_dpp v31, v27 row_shr:2 row_mask:0xf bank_mask:0xf
	v_pk_mul_f32 v[32:33], v[2:3], v[34:35]
	v_mov_b32_e32 v34, 1.0
	v_pk_fma_f32 v[2:3], v[2:3], v[30:31], v[26:27]
	v_mov_b32_e32 v26, v1
	v_mov_b32_e32 v35, 1.0
	v_mov_b32_e32 v27, v1
	v_mov_b32_dpp v34, v32 row_shr:4 row_mask:0xf bank_mask:0xf
	v_mov_b32_dpp v26, v2 row_shr:4 row_mask:0xf bank_mask:0xf
	v_mov_b32_dpp v35, v33 row_shr:4 row_mask:0xf bank_mask:0xf
	v_mov_b32_dpp v27, v3 row_shr:4 row_mask:0xf bank_mask:0xf
	v_pk_mul_f32 v[30:31], v[32:33], v[34:35]
	v_mov_b32_e32 v34, 1.0
	v_pk_fma_f32 v[2:3], v[32:33], v[26:27], v[2:3]
	v_mov_b32_e32 v26, v1
	v_mov_b32_e32 v27, v1
	v_mov_b32_e32 v35, 1.0
	v_mov_b32_dpp v34, v30 row_shr:8 row_mask:0xf bank_mask:0xf
	v_mov_b32_dpp v26, v2 row_shr:8 row_mask:0xf bank_mask:0xf
	v_mov_b32_dpp v27, v3 row_shr:8 row_mask:0xf bank_mask:0xf
	v_mov_b32_dpp v35, v31 row_shr:8 row_mask:0xf bank_mask:0xf
	v_pk_fma_f32 v[26:27], v[30:31], v[26:27], v[2:3]
	v_pk_mul_f32 v[30:31], v[30:31], v[34:35]
	s_and_saveexec_b64 s[0:1], s[18:19]
	s_cbranch_execz .LBB0_489
	ds_write_b128 v153, v[28:31] offset:37984
	ds_write_b128 v153, v[24:27] offset:38752
